# summary tile back block: stores 2/4/6 staged in a second quad so the seven store-data s_nop go (7 issue slots per tile)
# speedup vs baseline: 1.0032x; 1.0032x over previous
.LBB0_425:
	s_or_b64 exec, exec, s[34:35]
	s_waitcnt lgkmcnt(0)
	v_pk_add_f32 v[16:17], v[98:99], v[110:111]
	v_pk_add_f32 v[98:99], v[100:101], v[0:1]
	s_add_i32 s39, s39, 16
	v_pk_add_f32 v[2:3], v[102:103], v[2:3]
	v_cvt_pk_bf16_f32 v2, v2, v3
	v_pk_add_f32 v[4:5], v[106:107], v[4:5]
	v_cvt_pk_bf16_f32 v3, v4, v5
	v_pk_add_f32 v[6:7], v[108:109], v[6:7]
	v_lshl_add_u64 v[4:5], v[112:113], 0, s[18:19]
	v_pk_add_f32 v[10:11], v[92:93], v[10:11]
	s_add_u32 s30, s30, 0x800
	v_pk_add_f32 v[14:15], v[94:95], v[14:15]
	v_pk_add_f32 v[12:13], v[88:89], v[12:13]
	v_mov_b32_e32 v88, v89
	v_cvt_pk_bf16_f32 v0, v16, v17
	v_cvt_pk_bf16_f32 v1, v98, v99
	global_store_dwordx4 v[112:113], v[0:3], off sc1
	v_cvt_pk_bf16_f32 v170, v6, v7
	v_cvt_pk_bf16_f32 v171, v10, v11
	v_cvt_pk_bf16_f32 v172, v14, v15
	v_cvt_pk_bf16_f32 v173, v12, v13
	global_store_dwordx4 v[4:5], v[170:173], off sc1
	v_cvt_pk_bf16_f32 v0, v96, v97
	v_cvt_pk_bf16_f32 v1, v203, v204
	v_cvt_pk_bf16_f32 v2, v205, v207
	v_cvt_pk_bf16_f32 v3, v208, v212
	v_lshl_add_u64 v[4:5], v[112:113], 0, s[12:13]
	global_store_dwordx4 v[4:5], v[0:3], off sc1
	v_cvt_pk_bf16_f32 v170, v206, v209
	v_cvt_pk_bf16_f32 v171, v211, v213
	v_cvt_pk_bf16_f32 v172, v217, v218
	v_cvt_pk_bf16_f32 v173, v219, v90
	v_lshl_add_u64 v[4:5], v[112:113], 0, s[20:21]
	global_store_dwordx4 v[4:5], v[170:173], off sc1
	v_cvt_pk_bf16_f32 v0, v91, v118
	v_cvt_pk_bf16_f32 v1, v117, v116
	v_cvt_pk_bf16_f32 v2, v115, v114
	v_cvt_pk_bf16_f32 v3, v105, v104
	v_lshl_add_u64 v[4:5], v[112:113], 0, s[14:15]
	global_store_dwordx4 v[4:5], v[0:3], off sc1
	v_cvt_pk_bf16_f32 v170, v23, v22
	v_cvt_pk_bf16_f32 v171, v21, v20
	v_cvt_pk_bf16_f32 v172, v19, v18
	v_cvt_pk_bf16_f32 v173, v8, v9
	v_lshl_add_u64 v[4:5], v[112:113], 0, s[8:9]
	global_store_dwordx4 v[4:5], v[170:173], off sc1
	v_lshl_add_u64 v[0:1], v[112:113], 0, s[16:17]
	v_mov_b32_e32 v89, v110
	global_store_dwordx4 v[0:1], v[88:91], off sc1
	s_addc_u32 s31, s31, 0
	s_mov_b64 s[34:35], 0x1c00
	s_waitcnt vmcnt(7)
	v_lshl_add_u64 v[112:113], v[112:113], 0, s[34:35]
	s_cmpk_lg_i32 s30, 0x2000
	v_mov_b32_e32 v4, v201
	v_mov_b32_e32 v96, v198
	v_mov_b32_e32 v16, v200
	v_mov_b32_e32 v104, v197
	v_mov_b32_e32 v6, v199
	v_mov_b32_e32 v148, v202
	s_cbranch_scc0 .LBB0_393
